# phase 0: the 21 strided modulation-weight loads (75 MB read once per launch) marked non-temporal, on top of the non-temporal conversion loads
# speedup vs baseline: 1.0076x; 1.0004x over previous
; DI void phase_mod(const Params& p, unsigned char* lds, int tid) {
;     ...
;             for (int kb = kp * 147; kb < kp * 147 + 147; kb += 21) {
;                 float wv[21];
; #pragma unroll
;                 for (int q = 0; q < 21; ++q) { const int k = kb + q; wv[q] = (k < DM) ? w[(size_t)k * NMODW] : 0.f; }
.LBB0_1015:
	v_subrev_u32_e32 v29, 20, v27
	s_movk_i32 s4, 0x400
	v_cmp_gt_i32_e64 s[48:49], s4, v29
	v_mov_b32_e32 v60, 0
	s_and_saveexec_b64 s[4:5], s[48:49]
	s_cbranch_execz .LBB0_1017
	global_load_dword v60, v[4:5], off nt
.LBB0_1017:
	s_or_b64 exec, exec, s[4:5]
	v_subrev_u32_e32 v62, 19, v27
	v_cmp_gt_i32_e64 s[46:47], s3, v29
	v_mov_b32_e32 v54, 0
	v_mov_b32_e32 v58, 0
	s_and_saveexec_b64 s[4:5], s[46:47]
	s_cbranch_execz .LBB0_1019
	v_mad_i64_i32 v[30:31], s[8:9], v62, s68, v[2:3]
	global_load_dword v58, v[30:31], off nt
.LBB0_1019:
	s_or_b64 exec, exec, s[4:5]
	s_movk_i32 s4, 0x3fe
	v_subrev_u32_e32 v61, 18, v27
	v_cmp_gt_i32_e64 s[44:45], s4, v29
	s_and_saveexec_b64 s[4:5], s[44:45]
	s_cbranch_execz .LBB0_1021
	v_mad_i64_i32 v[30:31], s[8:9], v61, s68, v[2:3]
	global_load_dword v54, v[30:31], off nt
.LBB0_1021:
	s_or_b64 exec, exec, s[4:5]
	s_movk_i32 s4, 0x3fd
	v_subrev_u32_e32 v59, 17, v27
	v_cmp_gt_i32_e64 s[42:43], s4, v29
	v_mov_b32_e32 v50, 0
	v_mov_b32_e32 v55, 0
	s_and_saveexec_b64 s[4:5], s[42:43]
	s_cbranch_execz .LBB0_1023
	v_mad_i64_i32 v[30:31], s[8:9], v59, s68, v[2:3]
	global_load_dword v55, v[30:31], off nt
.LBB0_1023:
	s_or_b64 exec, exec, s[4:5]
	s_movk_i32 s4, 0x3fc
	v_add_u32_e32 v57, -16, v27
	v_cmp_gt_i32_e64 s[40:41], s4, v29
	s_and_saveexec_b64 s[4:5], s[40:41]
	s_cbranch_execz .LBB0_1025
	v_mad_i64_i32 v[30:31], s[8:9], v57, s68, v[2:3]
	global_load_dword v50, v[30:31], off nt
.LBB0_1025:
	s_or_b64 exec, exec, s[4:5]
	s_movk_i32 s4, 0x3fb
	v_add_u32_e32 v56, -15, v27
	v_cmp_gt_i32_e64 s[38:39], s4, v29
	v_mov_b32_e32 v39, 0
	v_mov_b32_e32 v51, 0
	s_and_saveexec_b64 s[4:5], s[38:39]
	s_cbranch_execz .LBB0_1027
	v_mad_i64_i32 v[30:31], s[8:9], v56, s68, v[2:3]
	global_load_dword v51, v[30:31], off nt
.LBB0_1027:
	s_or_b64 exec, exec, s[4:5]
	s_movk_i32 s4, 0x3fa
	v_add_u32_e32 v53, -14, v27
	v_cmp_gt_i32_e64 s[36:37], s4, v29
	s_and_saveexec_b64 s[4:5], s[36:37]
	s_cbranch_execz .LBB0_1029
	v_mad_i64_i32 v[30:31], s[8:9], v53, s68, v[2:3]
	global_load_dword v39, v[30:31], off nt
.LBB0_1029:
	s_or_b64 exec, exec, s[4:5]
	s_movk_i32 s4, 0x3f9
	v_add_u32_e32 v52, -13, v27
	v_cmp_gt_i32_e64 s[34:35], s4, v29
	v_mov_b32_e32 v34, 0
	v_mov_b32_e32 v46, 0
	s_and_saveexec_b64 s[4:5], s[34:35]
	s_cbranch_execz .LBB0_1031
	v_mad_i64_i32 v[30:31], s[8:9], v52, s68, v[2:3]
	global_load_dword v46, v[30:31], off nt
.LBB0_1031:
	s_or_b64 exec, exec, s[4:5]
	s_movk_i32 s4, 0x3f8
	v_add_u32_e32 v49, -12, v27
	v_cmp_gt_i32_e64 s[30:31], s4, v29
	s_and_saveexec_b64 s[4:5], s[30:31]
	s_cbranch_execz .LBB0_1033
	v_mad_i64_i32 v[30:31], s[8:9], v49, s68, v[2:3]
	global_load_dword v34, v[30:31], off nt
.LBB0_1033:
	s_or_b64 exec, exec, s[4:5]
	s_movk_i32 s4, 0x3f7
	v_add_u32_e32 v48, -11, v27
	v_cmp_gt_i32_e64 s[28:29], s4, v29
	v_mov_b32_e32 v35, 0
	v_mov_b32_e32 v36, 0
	s_and_saveexec_b64 s[4:5], s[28:29]
	s_cbranch_execz .LBB0_1035
	v_mad_i64_i32 v[30:31], s[8:9], v48, s68, v[2:3]
	global_load_dword v36, v[30:31], off nt
.LBB0_1035:
	s_or_b64 exec, exec, s[4:5]
	s_movk_i32 s4, 0x3f6
	v_add_u32_e32 v43, -10, v27
	v_cmp_gt_i32_e64 s[20:21], s4, v29
	s_and_saveexec_b64 s[4:5], s[20:21]
	s_cbranch_execz .LBB0_1037
	v_mad_i64_i32 v[30:31], s[8:9], v43, s68, v[2:3]
	global_load_dword v35, v[30:31], off nt
.LBB0_1037:
	s_or_b64 exec, exec, s[4:5]
	s_movk_i32 s4, 0x3f5
	v_add_u32_e32 v37, -9, v27
	v_cmp_gt_i32_e64 s[14:15], s4, v29
	v_mov_b32_e32 v14, 0
	v_mov_b32_e32 v16, 0
	s_and_saveexec_b64 s[4:5], s[14:15]
	s_cbranch_execz .LBB0_1039
	v_mad_i64_i32 v[30:31], s[8:9], v37, s68, v[2:3]
	global_load_dword v16, v[30:31], off nt
.LBB0_1039:
	s_or_b64 exec, exec, s[4:5]
	s_movk_i32 s4, 0x3f4
	v_add_u32_e32 v38, -8, v27
	v_cmp_gt_i32_e64 s[16:17], s4, v29
	s_and_saveexec_b64 s[4:5], s[16:17]
	s_cbranch_execz .LBB0_1041
	v_mad_i64_i32 v[30:31], s[8:9], v38, s68, v[2:3]
	global_load_dword v14, v[30:31], off nt
.LBB0_1041:
	s_or_b64 exec, exec, s[4:5]
	s_movk_i32 s4, 0x3f3
	v_add_u32_e32 v42, -7, v27
	v_cmp_gt_i32_e64 s[18:19], s4, v29
	v_mov_b32_e32 v18, 0
	v_mov_b32_e32 v20, 0
	s_and_saveexec_b64 s[4:5], s[18:19]
	s_cbranch_execz .LBB0_1043
	v_mad_i64_i32 v[30:31], s[8:9], v42, s68, v[2:3]
	global_load_dword v20, v[30:31], off nt
.LBB0_1043:
	s_or_b64 exec, exec, s[4:5]
	s_movk_i32 s4, 0x3f2
	v_add_u32_e32 v44, -6, v27
	v_cmp_gt_i32_e64 s[22:23], s4, v29
	s_and_saveexec_b64 s[4:5], s[22:23]
	s_cbranch_execz .LBB0_1045
	v_mad_i64_i32 v[30:31], s[8:9], v44, s68, v[2:3]
	global_load_dword v18, v[30:31], off nt
.LBB0_1045:
	s_or_b64 exec, exec, s[4:5]
	s_movk_i32 s4, 0x3f1
	v_add_u32_e32 v45, -5, v27
	v_cmp_gt_i32_e64 s[24:25], s4, v29
	v_mov_b32_e32 v22, 0
	v_mov_b32_e32 v24, 0
	s_and_saveexec_b64 s[4:5], s[24:25]
	s_cbranch_execz .LBB0_1047
	v_mad_i64_i32 v[30:31], s[8:9], v45, s68, v[2:3]
	global_load_dword v24, v[30:31], off nt
.LBB0_1047:
	s_or_b64 exec, exec, s[4:5]
	s_movk_i32 s4, 0x3f0
	v_add_u32_e32 v47, -4, v27
	v_cmp_gt_i32_e64 s[26:27], s4, v29
	s_and_saveexec_b64 s[4:5], s[26:27]
	s_cbranch_execz .LBB0_1049
	v_mad_i64_i32 v[30:31], s[8:9], v47, s68, v[2:3]
	global_load_dword v22, v[30:31], off nt
.LBB0_1049:
	s_or_b64 exec, exec, s[4:5]
	s_movk_i32 s4, 0x3ef
	v_add_u32_e32 v33, -3, v27
	v_cmp_gt_i32_e64 s[10:11], s4, v29
	v_mov_b32_e32 v26, 0
	v_mov_b32_e32 v28, 0
	s_and_saveexec_b64 s[4:5], s[10:11]
	s_cbranch_execz .LBB0_1051
	v_mad_i64_i32 v[30:31], s[8:9], v33, s68, v[2:3]
	global_load_dword v28, v[30:31], off nt
.LBB0_1051:
	s_or_b64 exec, exec, s[4:5]
	s_movk_i32 s4, 0x3ee
	v_add_u32_e32 v31, -2, v27
	v_cmp_gt_i32_e64 s[8:9], s4, v29
	s_and_saveexec_b64 s[4:5], s[8:9]
	s_cbranch_execz .LBB0_1053
	v_mad_i64_i32 v[40:41], s[12:13], v31, s68, v[2:3]
	global_load_dword v26, v[40:41], off nt
.LBB0_1053:
	s_or_b64 exec, exec, s[4:5]
	s_movk_i32 s4, 0x3ed
	v_add_u32_e32 v41, -1, v27
	v_cmp_gt_i32_e64 s[12:13], s4, v29
	v_mov_b32_e32 v40, 0
	v_mov_b32_e32 v30, 0
	s_and_saveexec_b64 s[4:5], s[12:13]
	s_cbranch_execz .LBB0_1055
	v_mad_i64_i32 v[64:65], s[52:53], v41, s68, v[2:3]
	global_load_dword v30, v[64:65], off nt
.LBB0_1055:
	s_or_b64 exec, exec, s[4:5]
	s_movk_i32 s4, 0x3ec
	v_cmp_gt_i32_e64 s[52:53], s4, v29
	v_mov_b32_e32 v32, 0
	s_and_saveexec_b64 s[4:5], s[52:53]
	s_cbranch_execz .LBB0_1014
	v_mad_i64_i32 v[64:65], s[52:53], v27, s68, v[2:3]
	global_load_dword v32, v[64:65], off nt
	v_mov_b32_e32 v40, v27
	s_branch .LBB0_1014
